# prologue balance: workgroups 0..31 (which also run the serial cpart jobs) skip the layer-0 MLP1 weight conversion; workgroups 32.. cover it
# speedup vs baseline: 1.0111x; 1.0111x over previous
.LBB0_45:
	s_load_dwordx2 s[52:53], s[0:1], 0xb8
	s_cmpk_lt_i32 s2, 0x1000
	v_mov_b32_e32 v2, v136
	s_cselect_b64 s[12:13], -1, 0
	s_cmpk_gt_i32 s2, 0xfff
	s_cbranch_scc1 .LBB0_57
	s_load_dwordx4 s[8:11], s[0:1], 0x78
	s_waitcnt lgkmcnt(0)
	s_cmp_lt_u32 s2, 32
	s_cbranch_scc1 .LBB0_57
	s_sub_i32 s64, s2, 32
	s_sub_i32 s65, s34, 32
	s_add_u32 s14, s52, 0x2800000
	s_addc_u32 s15, s53, 0
	v_ashrrev_i32_e32 v1, 3, v2
	v_lshlrev_b32_e32 v2, 3, v2
	v_and_b32_e32 v10, 56, v2
	s_cmp_lg_u64 s[8:9], 0
	s_cselect_b64 s[6:7], -1, 0
	s_movk_i32 s3, 0x104
	v_lshl_add_u32 v4, v1, 2, 16
	v_mul_u32_u24_e32 v5, 0x104, v10
	v_lshl_add_u32 v2, v10, 2, 16
	v_mul_lo_u32 v3, v1, s3
	v_cndmask_b32_e64 v6, 0, 1, s[6:7]
	v_add_u32_e32 v15, v4, v5
	v_mov_b32_e32 v13, 0
	s_lshl_b32 s3, s64, 6
	s_lshl_b32 s4, s65, 6
	v_cmp_ne_u32_e64 s[6:7], 1, v6
	s_movk_i32 s5, 0x2000
	v_add_u32_e32 v11, v2, v3
	v_lshlrev_b32_e32 v12, 1, v10
	v_add_u32_e32 v20, 0x400, v15
	s_mov_b32 s24, s64
	s_branch .LBB0_48
.LBB0_47:
	s_or_b64 exec, exec, s[22:23]
	s_add_i32 s24, s24, s65
	s_add_i32 s3, s3, s4
	s_cmpk_lt_i32 s24, 0x1000
	s_barrier
	s_cbranch_scc0 .LBB0_57
